# Prologue weight transpose: the 32 row loads of an item issued back to back from one running address instead of 32 masked blocks with aliasing 64-bit multiply address math
# speedup vs baseline: 1.0090x; 1.0090x over previous
; DI void transpose_item(const float* W, int K, int N, bf16_t* WT, int mode, const float* gk, const float* bk, float* p1, float* p2, LAS float* scr, int item, int lane) {
;     const int nblk = (N + 31) / 32, kb = item / nblk, nb = item % nblk, k0 = 64 * kb, n0 = 32 * nb;
;     const int n = n0 + (lane & 31);
;     float v[32];
; #pragma unroll
;     for (int i = 0; i < 32; ++i) { const int kk = 2 * i + (lane >> 5); v[i] = (n < N) ? W[(size_t)(k0 + kk) * N + n] : 0.f; }
; #pragma unroll
;     for (int i = 0; i < 32; ++i) { const int kk = 2 * i + (lane >> 5); scr[kk * 33 + (lane & 31)] = v[i]; }
;     asm volatile("s_waitcnt lgkmcnt(0)" ::: "memory");
.LBB0_591:
	s_waitcnt lgkmcnt(0)
	v_sub_u32_e32 v5, 0, v53
	v_max_i32_e32 v5, v53, v5
	v_mul_hi_u32 v6, v5, v54
	v_mul_lo_u32 v7, v6, s36
	v_sub_u32_e32 v5, v5, v7
	v_add_u32_e32 v7, 1, v6
	v_cmp_le_u32_e32 vcc, s36, v5
	v_ashrrev_i32_e32 v4, 31, v53
	v_mov_b32_e32 v9, 0
	v_cndmask_b32_e32 v6, v6, v7, vcc
	v_subrev_u32_e32 v7, s36, v5
	v_cndmask_b32_e32 v5, v5, v7, vcc
	v_add_u32_e32 v7, 1, v6
	v_cmp_le_u32_e32 vcc, s36, v5
	s_nop 1
	v_cndmask_b32_e32 v5, v6, v7, vcc
	v_xor_b32_e32 v5, v5, v4
	v_sub_u32_e32 v32, v5, v4
	v_mul_lo_u32 v22, s37, v32
	v_lshlrev_b32_e32 v20, 6, v32
	v_add3_u32 v4, v31, v55, v22
	v_or_b32_e32 v6, v20, v46
	v_ashrrev_i32_e32 v5, 31, v4
	v_cmp_gt_i32_e32 vcc, s34, v4
	v_lshl_add_u64 v[4:5], v[4:5], 2, s[14:15]
	v_mov_b32_e32 v7, 0
	v_ashrrev_i32_e32 v8, 31, v6
	v_mul_lo_u32 v10, v6, s34
	v_mov_b32_e32 v11, 0
	v_lshl_add_u64 v[4:5], v[10:11], 2, v[4:5]
	s_lshl_b32 s2, s34, 3
	s_mov_b32 s3, 0
	v_mov_b32_e32 v10, 0
	v_mov_b32_e32 v11, 0
	v_mov_b32_e32 v12, 0
	v_mov_b32_e32 v13, 0
	v_mov_b32_e32 v14, 0
	v_mov_b32_e32 v15, 0
	v_mov_b32_e32 v16, 0
	v_mov_b32_e32 v17, 0
	v_mov_b32_e32 v18, 0
	v_mov_b32_e32 v19, 0
	v_mov_b32_e32 v21, 0
	v_mov_b32_e32 v23, 0
	v_mov_b32_e32 v33, 0
	v_mov_b32_e32 v34, 0
	v_mov_b32_e32 v35, 0
	v_mov_b32_e32 v36, 0
	v_mov_b32_e32 v37, 0
	v_mov_b32_e32 v38, 0
	v_mov_b32_e32 v39, 0
	v_mov_b32_e32 v40, 0
	v_mov_b32_e32 v41, 0
	v_mov_b32_e32 v42, 0
	v_mov_b32_e32 v43, 0
	v_mov_b32_e32 v44, 0
	v_mov_b32_e32 v45, 0
	v_mov_b32_e32 v56, 0
	v_mov_b32_e32 v57, 0
	v_mov_b32_e32 v58, 0
	v_mov_b32_e32 v59, 0
	v_mov_b32_e32 v60, 0
	s_and_saveexec_b64 s[0:1], vcc
	global_load_dword v9, v[4:5], off
	v_lshl_add_u64 v[4:5], v[4:5], 0, s[2:3]
	global_load_dword v7, v[4:5], off
	v_lshl_add_u64 v[4:5], v[4:5], 0, s[2:3]
	global_load_dword v11, v[4:5], off
	v_lshl_add_u64 v[4:5], v[4:5], 0, s[2:3]
	global_load_dword v10, v[4:5], off
	v_lshl_add_u64 v[4:5], v[4:5], 0, s[2:3]
	global_load_dword v13, v[4:5], off
	v_lshl_add_u64 v[4:5], v[4:5], 0, s[2:3]
	global_load_dword v12, v[4:5], off
	v_lshl_add_u64 v[4:5], v[4:5], 0, s[2:3]
	global_load_dword v15, v[4:5], off
	v_lshl_add_u64 v[4:5], v[4:5], 0, s[2:3]
	global_load_dword v14, v[4:5], off
	v_lshl_add_u64 v[4:5], v[4:5], 0, s[2:3]
	global_load_dword v17, v[4:5], off
	v_lshl_add_u64 v[4:5], v[4:5], 0, s[2:3]
	global_load_dword v16, v[4:5], off
	v_lshl_add_u64 v[4:5], v[4:5], 0, s[2:3]
	global_load_dword v19, v[4:5], off
	v_lshl_add_u64 v[4:5], v[4:5], 0, s[2:3]
	global_load_dword v18, v[4:5], off
	v_lshl_add_u64 v[4:5], v[4:5], 0, s[2:3]
	global_load_dword v23, v[4:5], off
	v_lshl_add_u64 v[4:5], v[4:5], 0, s[2:3]
	global_load_dword v21, v[4:5], off
	v_lshl_add_u64 v[4:5], v[4:5], 0, s[2:3]
	global_load_dword v34, v[4:5], off
	v_lshl_add_u64 v[4:5], v[4:5], 0, s[2:3]
	global_load_dword v33, v[4:5], off
	v_lshl_add_u64 v[4:5], v[4:5], 0, s[2:3]
	global_load_dword v36, v[4:5], off
	v_lshl_add_u64 v[4:5], v[4:5], 0, s[2:3]
	global_load_dword v35, v[4:5], off
	v_lshl_add_u64 v[4:5], v[4:5], 0, s[2:3]
	global_load_dword v38, v[4:5], off
	v_lshl_add_u64 v[4:5], v[4:5], 0, s[2:3]
	global_load_dword v37, v[4:5], off
	v_lshl_add_u64 v[4:5], v[4:5], 0, s[2:3]
	global_load_dword v40, v[4:5], off
	v_lshl_add_u64 v[4:5], v[4:5], 0, s[2:3]
	global_load_dword v39, v[4:5], off
	v_lshl_add_u64 v[4:5], v[4:5], 0, s[2:3]
	global_load_dword v42, v[4:5], off
	v_lshl_add_u64 v[4:5], v[4:5], 0, s[2:3]
	global_load_dword v41, v[4:5], off
	v_lshl_add_u64 v[4:5], v[4:5], 0, s[2:3]
	global_load_dword v44, v[4:5], off
	v_lshl_add_u64 v[4:5], v[4:5], 0, s[2:3]
	global_load_dword v43, v[4:5], off
	v_lshl_add_u64 v[4:5], v[4:5], 0, s[2:3]
	global_load_dword v56, v[4:5], off
	v_lshl_add_u64 v[4:5], v[4:5], 0, s[2:3]
	global_load_dword v45, v[4:5], off
	v_lshl_add_u64 v[4:5], v[4:5], 0, s[2:3]
	global_load_dword v58, v[4:5], off
	v_lshl_add_u64 v[4:5], v[4:5], 0, s[2:3]
	global_load_dword v57, v[4:5], off
	v_lshl_add_u64 v[4:5], v[4:5], 0, s[2:3]
	global_load_dword v60, v[4:5], off
	v_lshl_add_u64 v[4:5], v[4:5], 0, s[2:3]
	global_load_dword v59, v[4:5], off
	s_or_b64 exec, exec, s[0:1]
	v_add_u32_e32 v4, 0x400, v52
	s_waitcnt vmcnt(0)
	ds_write2_b32 v52, v9, v7 offset1:66
	ds_write2_b32 v52, v11, v10 offset0:132 offset1:198
	ds_write2_b32 v4, v13, v12 offset0:8 offset1:74
	ds_write2_b32 v4, v15, v14 offset0:140 offset1:206
	v_add_u32_e32 v4, 0x800, v52
	ds_write2_b32 v4, v17, v16 offset0:16 offset1:82
	ds_write2_b32 v4, v19, v18 offset0:148 offset1:214
	v_add_u32_e32 v4, 0xc00, v52
	ds_write2_b32 v4, v23, v21 offset0:24 offset1:90
	ds_write2_b32 v4, v34, v33 offset0:156 offset1:222
	v_add_u32_e32 v4, 0x1000, v52
	ds_write2_b32 v4, v36, v35 offset0:32 offset1:98
	ds_write2_b32 v4, v38, v37 offset0:164 offset1:230
	v_add_u32_e32 v4, 0x1400, v52
	ds_write2_b32 v4, v40, v39 offset0:40 offset1:106
	ds_write2_b32 v4, v42, v41 offset0:172 offset1:238
	v_add_u32_e32 v4, 0x1800, v52
	ds_write2_b32 v4, v44, v43 offset0:48 offset1:114
	ds_write2_b32 v4, v56, v45 offset0:180 offset1:246
	v_add_u32_e32 v4, 0x1c00, v52
	ds_write2_b32 v4, v58, v57 offset0:56 offset1:122
	ds_write2_b32 v4, v60, v59 offset0:188 offset1:254
	s_waitcnt lgkmcnt(0)
	s_andn2_b64 vcc, exec, s[24:25]
	v_ashrrev_i32_e32 v21, 31, v20
	s_cbranch_vccnz .LBB0_658
	v_lshl_add_u64 v[4:5], v[20:21], 2, v[24:25]
	global_load_dwordx4 v[12:15], v[4:5], off offset:16
	global_load_dwordx4 v[16:19], v[4:5], off
	s_andn2_b64 vcc, exec, s[26:27]
	s_cbranch_vccnz .LBB0_659
